# attention loop: redundant vmcnt(4)/(2)/(1)/(0) ladder before the K/V ds_writes deleted (explicit asm vmcnt(0) already covers it), on top of v14
# speedup vs baseline: 1.0048x; 1.0016x over previous
; #define MFMA32(a, b, c) __builtin_amdgcn_mfma_f32_32x32x16_bf16((a), (b), (c), 0, 0, 0)
; DI void a_finishSM(f32x16& p0, f32x16& p1, float alpha, float& l_reg, bf16x8& pa0, bf16x8& pa1, bf16x8& pa2, bf16x8& pa3) {
; #pragma unroll
;   for (int r = 0; r < 16; ++r) p1[r] = __builtin_amdgcn_exp2f(p1[r]);
;   float ps = 0;
; #pragma unroll
;   for (int r = 0; r < 16; ++r) ps += p0[r];
; #pragma unroll
;   for (int r = 0; r < 16; ++r) ps += p1[r];
;   { auto rr = __builtin_amdgcn_permlane32_swap(__float_as_uint(ps), __float_as_uint(ps), false, false);
;     ps = __uint_as_float(rr[0]) + __uint_as_float(rr[1]); }
;   l_reg = l_reg * alpha + ps;
;     ...
;   PK4(p0, 0, pa0); PK4(p0, 8, pa1); PK4(p1, 0, pa2); PK4(p1, 8, pa3);
;     ...
; }
; DI void a_qkt(f32x16& p0, f32x16& p1, const char* Ks, const char* Ps, const bf16x8* qr, const char* QP, int r32, int hi) {
;   p0 = f32x16{}; p1 = f32x16{};
; #pragma unroll
;   for (int d0 = 0; d0 < 8; ++d0) { const int cb = (d0 * 16 + hi * 8) * 2;
;     bf16x8 b0 = *reinterpret_cast<const bf16x8*>(Ks + KSWZ(r32, cb));
;     bf16x8 b1 = *reinterpret_cast<const bf16x8*>(Ks + KSWZ(32 + r32, cb));
;     p0 = MFMA32(b0, qr[d0], p0);
;     p1 = MFMA32(b1, qr[d0], p1); }
; #pragma unroll
;   for (int d0 = 0; d0 < 4; ++d0) { const int cb = (d0 * 16 + hi * 8) * 2;
;     bf16x8 b0 = *reinterpret_cast<const bf16x8*>(Ps + PSWZ(r32, cb));
;     bf16x8 b1 = *reinterpret_cast<const bf16x8*>(Ps + PSWZ(32 + r32, cb));
;     const bf16x8 qp = *reinterpret_cast<const bf16x8*>(QP + d0 * 1024);
;     p0 = MFMA32(b0, qp, p0);
;     p1 = MFMA32(b1, qp, p1); }
; }
.LBB0_665:
	s_mov_b32 s8, s4
	s_add_i32 s4, s7, 0
	v_add_u32_e32 v70, s4, v170
	ds_read_b128 v[66:69], v70 offset:16384
	ds_read_b128 v[82:85], v70 offset:24576
	v_add_u32_e32 v166, s4, v172
	ds_read_b128 v[202:205], v166 offset:16384
	ds_read_b128 v[206:209], v166 offset:24576
	s_waitcnt lgkmcnt(3)
	v_mfma_f32_32x32x16_bf16 v[66:81], v[66:69], v[114:117], 0
	v_exp_f32_e32 v185, v130
	v_exp_f32_e32 v186, v131
	s_waitcnt lgkmcnt(2)
	v_mfma_f32_32x32x16_bf16 v[82:97], v[82:85], v[114:117], 0
	v_add_u32_e32 v166, s4, v173
	ds_read_b128 v[214:217], v166 offset:16384
	ds_read_b128 v[218:221], v166 offset:24576
	v_exp_f32_e32 v187, v146
	v_exp_f32_e32 v188, v147
	s_waitcnt lgkmcnt(3)
	v_mfma_f32_32x32x16_bf16 v[66:81], v[202:205], v[118:121], v[66:81]
	v_exp_f32_e32 v189, v132
	v_exp_f32_e32 v190, v133
	s_waitcnt lgkmcnt(2)
	v_mfma_f32_32x32x16_bf16 v[82:97], v[206:209], v[118:121], v[82:97]
	v_add_u32_e32 v166, s4, v174
	ds_read_b128 v[202:205], v166 offset:16384
	ds_read_b128 v[206:209], v166 offset:24576
	v_exp_f32_e32 v191, v148
	v_exp_f32_e32 v192, v149
	s_waitcnt lgkmcnt(3)
	v_mfma_f32_32x32x16_bf16 v[66:81], v[214:217], v[126:129], v[66:81]
	v_exp_f32_e32 v193, v150
	v_add_f32_e32 v201, 0, v240
	v_add_f32_e32 v201, v241, v201
	s_waitcnt lgkmcnt(2)
	v_mfma_f32_32x32x16_bf16 v[82:97], v[218:221], v[126:129], v[82:97]
	v_add_u32_e32 v166, s4, v175
	ds_read_b128 v[214:217], v166 offset:16384
	ds_read_b128 v[218:221], v166 offset:24576
	v_exp_f32_e32 v194, v151
	v_add_f32_e32 v201, v242, v201
	v_add_f32_e32 v201, v243, v201
	s_waitcnt lgkmcnt(3)
	v_mfma_f32_32x32x16_bf16 v[66:81], v[202:205], v[122:125], v[66:81]
	v_exp_f32_e32 v195, v154
	v_add_f32_e32 v201, v244, v201
	v_add_f32_e32 v201, v245, v201
	s_waitcnt lgkmcnt(2)
	v_mfma_f32_32x32x16_bf16 v[82:97], v[206:209], v[122:125], v[82:97]
	v_add_u32_e32 v166, s4, v176
	ds_read_b128 v[202:205], v166 offset:16384
	ds_read_b128 v[206:209], v166 offset:24576
	v_exp_f32_e32 v196, v155
	v_add_f32_e32 v201, v246, v201
	v_add_f32_e32 v201, v247, v201
	s_waitcnt lgkmcnt(3)
	v_mfma_f32_32x32x16_bf16 v[66:81], v[214:217], v[110:113], v[66:81]
	v_exp_f32_e32 v197, v152
	v_add_f32_e32 v201, v248, v201
	v_add_f32_e32 v201, v249, v201
	s_waitcnt lgkmcnt(2)
	v_mfma_f32_32x32x16_bf16 v[82:97], v[218:221], v[110:113], v[82:97]
	v_add_u32_e32 v166, s4, v177
	ds_read_b128 v[214:217], v166 offset:16384
	ds_read_b128 v[218:221], v166 offset:24576
	v_exp_f32_e32 v198, v153
	v_add_f32_e32 v201, v250, v201
	v_add_f32_e32 v201, v251, v201
	s_waitcnt lgkmcnt(3)
	v_mfma_f32_32x32x16_bf16 v[66:81], v[202:205], v[106:109], v[66:81]
	v_exp_f32_e32 v199, v156
	v_add_f32_e32 v201, v252, v201
	v_add_f32_e32 v201, v253, v201
	s_waitcnt lgkmcnt(2)
	v_mfma_f32_32x32x16_bf16 v[82:97], v[206:209], v[106:109], v[82:97]
	v_add_u32_e32 v166, s4, v178
	ds_read_b128 v[202:205], v166 offset:16384
	ds_read_b128 v[206:209], v166 offset:24576
	v_exp_f32_e32 v200, v157
	v_add_f32_e32 v201, v254, v201
	v_add_f32_e32 v201, v255, v201
	s_waitcnt lgkmcnt(3)
	v_mfma_f32_32x32x16_bf16 v[66:81], v[214:217], v[102:105], v[66:81]
	v_add_f32_e32 v201, v185, v201
	v_add_f32_e32 v201, v186, v201
	v_cvt_pk_bf16_f32 v130, v240, v241
	s_waitcnt lgkmcnt(2)
	v_mfma_f32_32x32x16_bf16 v[82:97], v[218:221], v[102:105], v[82:97]
	v_add_u32_e32 v166, s4, v179
	ds_read_b128 v[214:217], v166 offset:32768
	ds_read_b128 v[218:221], v166 offset:36864
	ds_read_b128 v[222:225], v163
	v_add_f32_e32 v201, v187, v201
	v_add_f32_e32 v201, v188, v201
	v_cvt_pk_bf16_f32 v131, v242, v243
	s_waitcnt lgkmcnt(4)
	v_mfma_f32_32x32x16_bf16 v[66:81], v[202:205], v[98:101], v[66:81]
	v_add_f32_e32 v201, v189, v201
	v_add_f32_e32 v201, v190, v201
	v_cvt_pk_bf16_f32 v132, v244, v245
	s_waitcnt lgkmcnt(3)
	v_mfma_f32_32x32x16_bf16 v[82:97], v[206:209], v[98:101], v[82:97]
	v_add_u32_e32 v166, s4, v180
	ds_read_b128 v[202:205], v166 offset:32768
	ds_read_b128 v[206:209], v166 offset:36864
	ds_read_b128 v[210:213], v163 offset:1024
	v_add_f32_e32 v201, v191, v201
	v_add_f32_e32 v201, v192, v201
	v_cvt_pk_bf16_f32 v133, v246, v247
	s_waitcnt lgkmcnt(3)
	v_mfma_f32_32x32x16_bf16 v[66:81], v[214:217], v[222:225], v[66:81]
	v_add_f32_e32 v201, v193, v201
	v_add_f32_e32 v201, v194, v201
	v_cvt_pk_bf16_f32 v154, v248, v249
	v_mfma_f32_32x32x16_bf16 v[82:97], v[218:221], v[222:225], v[82:97]
	v_add_u32_e32 v166, s4, v181
	ds_read_b128 v[214:217], v166 offset:32768
	ds_read_b128 v[218:221], v166 offset:36864
	ds_read_b128 v[222:225], v163 offset:2048
	v_add_f32_e32 v201, v195, v201
	v_add_f32_e32 v201, v196, v201
	v_cvt_pk_bf16_f32 v155, v250, v251
	s_waitcnt lgkmcnt(3)
	v_mfma_f32_32x32x16_bf16 v[66:81], v[202:205], v[210:213], v[66:81]
	v_add_f32_e32 v201, v197, v201
	v_add_f32_e32 v201, v198, v201
	v_cvt_pk_bf16_f32 v156, v252, v253
	v_mfma_f32_32x32x16_bf16 v[82:97], v[206:209], v[210:213], v[82:97]
	v_add_u32_e32 v166, s4, v182
	ds_read_b128 v[202:205], v166 offset:32768
	ds_read_b128 v[206:209], v166 offset:36864
	ds_read_b128 v[210:213], v163 offset:3072
	v_add_f32_e32 v201, v199, v201
	v_add_f32_e32 v150, v200, v201
	v_cvt_pk_bf16_f32 v157, v254, v255
	s_waitcnt lgkmcnt(3)
	v_mfma_f32_32x32x16_bf16 v[66:81], v[214:217], v[222:225], v[66:81]
	v_mov_b32_e32 v151, v150
	v_cvt_pk_bf16_f32 v184, v185, v186
	v_cvt_pk_bf16_f32 v185, v187, v188
	v_permlane32_swap_b32_e32 v130, v132
	v_mfma_f32_32x32x16_bf16 v[82:97], v[218:221], v[222:225], v[82:97]
	v_add_u32_e32 v166, s8, v171
	ds_read_b64_tr_b16 v[214:215], v166 offset:2048
	ds_read_b64_tr_b16 v[216:217], v166 offset:4096
	ds_read_b64_tr_b16 v[218:219], v166 offset:6144
	ds_read_b64_tr_b16 v[220:221], v166 offset:8192
	ds_read_b64_tr_b16 v[222:223], v166 offset:10240
	ds_read_b64_tr_b16 v[224:225], v166 offset:12288
	ds_read_b64_tr_b16 v[226:227], v166 offset:14336
	v_cvt_pk_bf16_f32 v186, v189, v190
	v_cvt_pk_bf16_f32 v187, v191, v192
	v_permlane32_swap_b32_e32 v150, v151
	v_permlane32_swap_b32_e32 v131, v133
	s_waitcnt lgkmcnt(7)
; #define SBAR() __builtin_amdgcn_sched_barrier(0)
; #define SLOAD(k0) do { vs0 = *(const bf16x8*)(&Vh[(long)((k0) + sr) * LDK + sc]); vs1 = *(const bf16x8*)(&Vh[(long)((k0) + 32 + sr) * LDK + sc]); \
;     ks0 = *(const bf16x8*)(&Kh[(long)((k0) + sr) * LDK + sc]); ks1 = *(const bf16x8*)(&Kh[(long)((k0) + 32 + sr) * LDK + sc]); \
;     ps0 = *(const bf16x8*)(&Ph[(long)((k0) + pr) * LDP + pc]); } while (0)
; #define SWAIT() asm volatile("s_waitcnt vmcnt(0)" ::: "memory")
; DI void pv_sm(f32x16* o, int vb, bf16x8 pa0, bf16x8 pa1, bf16x8 pa2, bf16x8 pa3, f32x16& p0, f32x16& p1, float& m_reg, float& mn, float& alpha) {
;   PV_BLOCK(0)
;   float pm0 = p0[0];
; #pragma unroll
;   for (int r = 1; r < 16; ++r) pm0 = fmaxf(pm0, p0[r]);
;   PV_BLOCK(1)
;   float pmax = pm0;
; #pragma unroll
;   for (int r = 0; r < 16; ++r) pmax = fmaxf(pmax, p1[r]);
;   { auto rr = __builtin_amdgcn_permlane32_swap(__float_as_uint(pmax), __float_as_uint(pmax), false, false);
;     pmax = fmaxf(__uint_as_float(rr[0]), __uint_as_float(rr[1])); }
;   const bool keep = __all(pmax - m_reg <= ATH);
;   mn = keep ? m_reg : fmaxf(m_reg, pmax);
;   alpha = __builtin_amdgcn_exp2f(m_reg - mn);
;   m_reg = mn;
;   PV_BLOCK(2)
; #pragma unroll
;   for (int r = 0; r < 16; ++r) { p0[r] = p0[r] - mn; p1[r] = p1[r] - mn; }
;   PV_BLOCK(3)
; #pragma unroll
;   for (int r = 0; r < 16; ++r) p0[r] = __builtin_amdgcn_exp2f(p0[r]);
; }
; DI void attn_unit(const bf16_t* __restrict__ Qb, const bf16_t* __restrict__ Kh, const bf16_t* __restrict__ Vh, const bf16_t* __restrict__ Ph,
;                   bf16_t* __restrict__ Ob, int seq, float* __restrict__ lse_out, char* lds) {
;     ...
;   f32x16 pA0, pA1, pB0, pB1; float mnA, mnB, alA, alB; bf16x8 pa0, pa1, pa2, pa3; const int NT = seq / 64;
;   SLOAD(0); SWAIT(); SWRITE(0); __syncthreads();
;   a_qkt(pA0, pA1, lds + A_KO, lds + A_PO, qr, QP, r32, hi); a_partialSM(pA0, pA1, m_reg, mnA, alA);
;   SLOAD(64);
;   SWAIT(); SWRITE(A_STG); __syncthreads();
;   int sV = 0, sK = A_STG, sW = 2 * A_STG;
;   for (int j = 1; j + 1 < NT; j += 2) {
;     SBAR(); a_qkt(pB0, pB1, lds + sK + A_KO, lds + sK + A_PO, qr, QP, r32, hi);
;     a_finishSM(pA0, pA1, alA, l_reg, pa0, pa1, pa2, pa3); SBAR();
;     SLOAD((j + 1) * 64); SBAR();
;     pv_sm(o, vb0 + sV, pa0, pa1, pa2, pa3, pB0, pB1, m_reg, mnB, alB);
;     SWAIT(); SWRITE(sW);
;     RESC(alB); __syncthreads();
	v_mfma_f32_32x32x16_bf16 v[66:81], v[202:205], v[210:213], v[66:81]
	v_cvt_pk_bf16_f32 v188, v193, v194
	v_cvt_pk_bf16_f32 v189, v195, v196
	v_permlane32_swap_b32_e32 v154, v156
	v_mfma_f32_32x32x16_bf16 v[82:97], v[206:209], v[210:213], v[82:97]
	ds_read_b64_tr_b16 v[212:213], v166 offset:0
	v_cvt_pk_bf16_f32 v190, v197, v198
	v_cvt_pk_bf16_f32 v191, v199, v200
	v_permlane32_swap_b32_e32 v155, v157
	s_nop 0
	v_permlane32_swap_b32_e32 v184, v186
	v_permlane32_swap_b32_e32 v185, v187
	v_permlane32_swap_b32_e32 v188, v190
	v_permlane32_swap_b32_e32 v189, v191
	v_lshl_add_u64 v[146:147], s[84:85], 0, v[142:143]
	v_add_co_u32_e32 v148, vcc, s56, v146
	s_nop 1
	v_addc_co_u32_e32 v149, vcc, 0, v147, vcc
	v_add_co_u32_e32 v152, vcc, s57, v146
	s_nop 1
	v_addc_co_u32_e32 v153, vcc, 0, v147, vcc
	global_load_dwordx4 v[192:195], v[148:149], off offset:256
	global_load_dwordx4 v[196:199], v[148:149], off
	global_load_dwordx4 v[200:203], v[152:153], off offset:256
	global_load_dwordx4 v[204:207], v[152:153], off
	v_lshl_add_u64 v[148:149], s[84:85], 0, v[140:141]
	v_add_co_u32_e32 v152, vcc, s58, v148
	s_nop 1
	v_addc_co_u32_e32 v153, vcc, 0, v149, vcc
	global_load_dwordx4 v[208:211], v[152:153], off
	v_add_u32_e32 v166, s8, v171
	s_waitcnt lgkmcnt(0)
	s_nop 0
	v_mfma_f32_32x32x16_bf16 v[2:17], v[130:133], v[212:215], v[2:17]
	ds_read_b64_tr_b16 v[212:213], v166 offset:0x200
	ds_read_b64_tr_b16 v[214:215], v166 offset:0xa00
	v_max_f32_e32 v152, v67, v67
	v_max_f32_e32 v153, v66, v66
	v_max_f32_e32 v152, v153, v152
	v_max3_f32 v152, v152, v68, v69
	v_max3_f32 v152, v152, v70, v71
	v_mfma_f32_32x32x16_bf16 v[2:17], v[154:157], v[216:219], v[2:17]
	ds_read_b64_tr_b16 v[216:217], v166 offset:0x1200
	ds_read_b64_tr_b16 v[218:219], v166 offset:0x1a00
	v_max3_f32 v152, v152, v72, v73
	v_max3_f32 v152, v152, v74, v75
	v_max3_f32 v152, v152, v76, v77
	v_max3_f32 v152, v152, v78, v79
	v_max3_f32 v152, v152, v80, v81
	v_mfma_f32_32x32x16_bf16 v[2:17], v[184:187], v[220:223], v[2:17]
	ds_read_b64_tr_b16 v[220:221], v166 offset:0x2200
	ds_read_b64_tr_b16 v[222:223], v166 offset:0x2a00
	ds_read_b64_tr_b16 v[228:229], v166 offset:0x3200
	ds_read_b64_tr_b16 v[230:231], v166 offset:0x3a00
	v_mfma_f32_32x32x16_bf16 v[2:17], v[188:191], v[224:227], v[2:17]
	s_waitcnt lgkmcnt(0)
	v_mfma_f32_32x32x16_bf16 v[50:65], v[130:133], v[212:215], v[50:65]
	v_max3_f32 v152, v152, v82, v83
	v_max3_f32 v152, v152, v84, v85
	v_max3_f32 v152, v152, v86, v87
	v_max3_f32 v152, v152, v88, v89
	v_max3_f32 v152, v152, v90, v91
	v_max3_f32 v152, v152, v92, v93
	v_max3_f32 v152, v152, v94, v95
	v_mfma_f32_32x32x16_bf16 v[50:65], v[154:157], v[216:219], v[50:65]
	v_max3_f32 v152, v152, v96, v97
	v_mov_b32_e32 v153, v152
	s_nop 1
	v_permlane32_swap_b32_e32 v152, v153
	v_max_f32_e32 v153, v153, v153
	v_max_f32_e32 v152, v152, v152
	v_max_f32_e32 v152, v152, v153
	v_mfma_f32_32x32x16_bf16 v[50:65], v[184:187], v[220:223], v[50:65]
	ds_read_b64_tr_b16 v[212:213], v166 offset:0x400
	v_sub_f32_e32 v153, v152, v144
	ds_read_b64_tr_b16 v[214:215], v166 offset:0xc00
	v_cmp_ge_f32_e32 vcc, s54, v153
	ds_read_b64_tr_b16 v[216:217], v166 offset:0x1400
	s_cmp_eq_u64 vcc, exec
	v_max_f32_e32 v153, v144, v144
	ds_read_b64_tr_b16 v[218:219], v166 offset:0x1c00
	ds_read_b64_tr_b16 v[220:221], v166 offset:0x2400
	ds_read_b64_tr_b16 v[222:223], v166 offset:0x2c00
	ds_read_b64_tr_b16 v[224:225], v166 offset:0x3400
	ds_read_b64_tr_b16 v[226:227], v166 offset:0x3c00
	v_mfma_f32_32x32x16_bf16 v[50:65], v[188:191], v[228:231], v[50:65]
	v_max_f32_e32 v152, v153, v152
	s_cselect_b64 vcc, -1, 0
	v_cndmask_b32_e32 v153, v152, v144, vcc
	v_sub_f32_e32 v144, v144, v153
	v_exp_f32_e32 v152, v144
	s_waitcnt lgkmcnt(0)
	v_mfma_f32_32x32x16_bf16 v[34:49], v[130:133], v[212:215], v[34:49]
	ds_read_b64_tr_b16 v[212:213], v166 offset:0x600
	ds_read_b64_tr_b16 v[214:215], v166 offset:0xe00
	v_sub_f32_e32 v66, v66, v153
	v_sub_f32_e32 v67, v67, v153
	v_sub_f32_e32 v68, v68, v153
	v_sub_f32_e32 v69, v69, v153
	v_mfma_f32_32x32x16_bf16 v[34:49], v[154:157], v[216:219], v[34:49]
	ds_read_b64_tr_b16 v[216:217], v166 offset:0x1600
	ds_read_b64_tr_b16 v[218:219], v166 offset:0x1e00
	v_sub_f32_e32 v70, v70, v153
	v_sub_f32_e32 v71, v71, v153
	v_exp_f32_e32 v240, v66
	v_exp_f32_e32 v241, v67
	v_mfma_f32_32x32x16_bf16 v[34:49], v[184:187], v[220:223], v[34:49]
	ds_read_b64_tr_b16 v[220:221], v166 offset:0x2600
	ds_read_b64_tr_b16 v[222:223], v166 offset:0x2e00
	ds_read_b64_tr_b16 v[228:229], v166 offset:0x3600
	ds_read_b64_tr_b16 v[230:231], v166 offset:0x3e00
	v_mfma_f32_32x32x16_bf16 v[34:49], v[188:191], v[224:227], v[34:49]
	v_sub_f32_e32 v72, v72, v153
	v_sub_f32_e32 v73, v73, v153
	v_exp_f32_e32 v242, v68
	v_exp_f32_e32 v243, v69
	s_waitcnt lgkmcnt(0)
	v_sub_f32_e32 v74, v74, v153
	v_sub_f32_e32 v75, v75, v153
	v_exp_f32_e32 v244, v70
	v_exp_f32_e32 v245, v71
	v_mfma_f32_32x32x16_bf16 v[18:33], v[130:133], v[212:215], v[18:33]
	v_sub_f32_e32 v76, v76, v153
	v_sub_f32_e32 v77, v77, v153
	v_exp_f32_e32 v246, v72
	v_exp_f32_e32 v247, v73
	s_add_i32 s9, s6, 0
	v_add_u32_e32 v130, s9, v164
	s_waitcnt vmcnt(0)
	ds_write_b128 v130, v[192:195]
	v_add_u32_e32 v130, s9, v165
	ds_write_b128 v130, v[200:203]
	v_add_u32_e32 v130, s9, v167
	v_mfma_f32_32x32x16_bf16 v[18:33], v[154:157], v[216:219], v[18:33]
	ds_write_b128 v130, v[196:199] offset:16384
	v_add_u32_e32 v130, s9, v168
	ds_write_b128 v130, v[204:207] offset:16384
	v_add_u32_e32 v130, s9, v169
	v_cmp_gt_f32_e32 vcc, 1.0, v152
	ds_write_b128 v130, v[208:211] offset:32768
	v_sub_f32_e32 v78, v78, v153
	v_sub_f32_e32 v79, v79, v153
	v_exp_f32_e32 v248, v74
	v_exp_f32_e32 v249, v75
	v_mfma_f32_32x32x16_bf16 v[18:33], v[184:187], v[220:223], v[18:33]
	v_sub_f32_e32 v80, v80, v153
	v_sub_f32_e32 v81, v81, v153
	v_exp_f32_e32 v250, v76
	v_exp_f32_e32 v251, v77
	v_mfma_f32_32x32x16_bf16 v[18:33], v[188:191], v[228:231], v[18:33]
	v_exp_f32_e32 v252, v78
	v_exp_f32_e32 v253, v79
	v_exp_f32_e32 v254, v80
	v_exp_f32_e32 v255, v81
	s_cbranch_vccz .LBB0_669
; #define MFMA32(a, b, c) __builtin_amdgcn_mfma_f32_32x32x16_bf16((a), (b), (c), 0, 0, 0)
; #define SBAR() __builtin_amdgcn_sched_barrier(0)
; DI void a_qkt(f32x16& p0, f32x16& p1, const char* Ks, const char* Ps, const bf16x8* qr, const char* QP, int r32, int hi) {
;   p0 = f32x16{}; p1 = f32x16{};
; #pragma unroll
;   for (int d0 = 0; d0 < 8; ++d0) { const int cb = (d0 * 16 + hi * 8) * 2;
;     bf16x8 b0 = *reinterpret_cast<const bf16x8*>(Ks + KSWZ(r32, cb));
;     bf16x8 b1 = *reinterpret_cast<const bf16x8*>(Ks + KSWZ(32 + r32, cb));
;     p0 = MFMA32(b0, qr[d0], p0);
;     p1 = MFMA32(b1, qr[d0], p1); }
; #pragma unroll
;   for (int d0 = 0; d0 < 4; ++d0) { const int cb = (d0 * 16 + hi * 8) * 2;
;     bf16x8 b0 = *reinterpret_cast<const bf16x8*>(Ps + PSWZ(r32, cb));
;     bf16x8 b1 = *reinterpret_cast<const bf16x8*>(Ps + PSWZ(32 + r32, cb));
;     const bf16x8 qp = *reinterpret_cast<const bf16x8*>(QP + d0 * 1024);
;     p0 = MFMA32(b0, qp, p0);
;     p1 = MFMA32(b1, qp, p1); }
; }
; DI void attn_unit(const bf16_t* __restrict__ Qb, const bf16_t* __restrict__ Kh, const bf16_t* __restrict__ Vh, const bf16_t* __restrict__ Ph,
;                   bf16_t* __restrict__ Ob, int seq, float* __restrict__ lse_out, char* lds) {
;     ...
;   f32x16 pA0, pA1, pB0, pB1; float mnA, mnB, alA, alB; bf16x8 pa0, pa1, pa2, pa3; const int NT = seq / 64;
;   SLOAD(0); SWAIT(); SWRITE(0); __syncthreads();
;   a_qkt(pA0, pA1, lds + A_KO, lds + A_PO, qr, QP, r32, hi); a_partialSM(pA0, pA1, m_reg, mnA, alA);
;   SLOAD(64);
;   SWAIT(); SWRITE(A_STG); __syncthreads();
;   int sV = 0, sK = A_STG, sW = 2 * A_STG;
;   for (int j = 1; j + 1 < NT; j += 2) {
;     SBAR(); a_qkt(pB0, pB1, lds + sK + A_KO, lds + sK + A_PO, qr, QP, r32, hi);
;     a_finishSM(pA0, pA1, alA, l_reg, pa0, pa1, pa2, pa3); SBAR();
;     SLOAD((j + 1) * 64); SBAR();
;     pv_sm(o, vb0 + sV, pa0, pa1, pa2, pa3, pB0, pB1, m_reg, mnB, alB);
;     SWAIT(); SWRITE(sW);
;     RESC(alB); __syncthreads();
;     { const int t_ = sV; sV = sK; sK = sW; sW = t_; }
;     SBAR(); a_qkt(pA0, pA1, lds + sK + A_KO, lds + sK + A_PO, qr, QP, r32, hi);
;     a_finishSM(pB0, pB1, alB, l_reg, pa0, pa1, pa2, pa3); SBAR();
;     SLOAD((j + 2) * 64); SBAR();
;     pv_sm(o, vb0 + sV, pa0, pa1, pa2, pa3, pA0, pA1, m_reg, mnA, alA);
;     SWAIT(); SWRITE(sW);
;     RESC(alA); __syncthreads();
	s_and_saveexec_b64 s[4:5], s[2:3]
	ds_write_b32 v161, v152 offset:128
	s_or_b64 exec, exec, s[4:5]
	s_waitcnt lgkmcnt(0)
	v_add_u32_e32 v144, v137, v134
	ds_read_b128 v[130:133], v144 offset:224
	ds_read_b128 v[154:157], v144 offset:192
	ds_read_b128 v[184:187], v144 offset:160
	ds_read_b128 v[188:191], v144 offset:128
	s_waitcnt lgkmcnt(3)
	v_pk_mul_f32 v[14:15], v[14:15], v[130:131]
	s_waitcnt lgkmcnt(2)
	v_pk_mul_f32 v[10:11], v[10:11], v[154:155]
	s_waitcnt lgkmcnt(1)
	v_pk_mul_f32 v[6:7], v[6:7], v[184:185]
	v_pk_mul_f32 v[16:17], v[16:17], v[132:133]
	v_pk_mul_f32 v[12:13], v[12:13], v[156:157]
	v_pk_mul_f32 v[8:9], v[8:9], v[186:187]
	s_waitcnt lgkmcnt(0)
	v_pk_mul_f32 v[4:5], v[4:5], v[190:191]
	v_pk_mul_f32 v[2:3], v[2:3], v[188:189]
	v_pk_mul_f32 v[62:63], v[62:63], v[130:131]
	v_pk_mul_f32 v[58:59], v[58:59], v[154:155]
	v_pk_mul_f32 v[54:55], v[54:55], v[184:185]
	v_pk_mul_f32 v[64:65], v[64:65], v[132:133]
	v_pk_mul_f32 v[60:61], v[60:61], v[156:157]
	v_pk_mul_f32 v[56:57], v[56:57], v[186:187]
	v_pk_mul_f32 v[52:53], v[52:53], v[190:191]
	v_pk_mul_f32 v[50:51], v[50:51], v[188:189]
	v_pk_mul_f32 v[46:47], v[46:47], v[130:131]
	v_pk_mul_f32 v[42:43], v[42:43], v[154:155]
	v_pk_mul_f32 v[38:39], v[38:39], v[184:185]
	v_pk_mul_f32 v[48:49], v[48:49], v[132:133]
	v_pk_mul_f32 v[44:45], v[44:45], v[156:157]
	v_pk_mul_f32 v[40:41], v[40:41], v[186:187]
	v_pk_mul_f32 v[36:37], v[36:37], v[190:191]
	v_pk_mul_f32 v[34:35], v[34:35], v[188:189]
	v_pk_mul_f32 v[30:31], v[30:31], v[130:131]
	v_pk_mul_f32 v[26:27], v[26:27], v[154:155]
	v_pk_mul_f32 v[22:23], v[22:23], v[184:185]
	v_pk_mul_f32 v[32:33], v[32:33], v[132:133]
	v_pk_mul_f32 v[28:29], v[28:29], v[156:157]
	v_pk_mul_f32 v[24:25], v[24:25], v[186:187]
	v_pk_mul_f32 v[20:21], v[20:21], v[190:191]
	v_pk_mul_f32 v[18:19], v[18:19], v[188:189]
.LBB0_669:
	s_waitcnt lgkmcnt(0)
	s_barrier
	v_add_u32_e32 v70, s9, v170
	ds_read_b128 v[66:69], v70 offset:16384
	ds_read_b128 v[70:73], v70 offset:24576
	v_add_u32_e32 v226, s9, v172
	ds_read_b128 v[204:207], v226 offset:16384
	ds_read_b128 v[208:211], v226 offset:24576
	v_sub_f32_e32 v144, v82, v153
	v_sub_f32_e32 v188, v83, v153
	v_sub_f32_e32 v189, v84, v153
	v_sub_f32_e32 v190, v85, v153
	v_sub_f32_e32 v191, v86, v153
	v_sub_f32_e32 v192, v87, v153
	v_sub_f32_e32 v193, v88, v153
	v_sub_f32_e32 v194, v89, v153
	v_sub_f32_e32 v195, v90, v153
	v_sub_f32_e32 v196, v91, v153
	v_sub_f32_e32 v197, v92, v153
	v_sub_f32_e32 v198, v93, v153
	v_sub_f32_e32 v199, v94, v153
	v_sub_f32_e32 v200, v95, v153
	v_sub_f32_e32 v201, v96, v153
	v_sub_f32_e32 v202, v97, v153
	s_waitcnt lgkmcnt(3)
	v_mfma_f32_32x32x16_bf16 v[82:97], v[66:69], v[114:117], 0
	v_exp_f32_e32 v144, v144
	v_exp_f32_e32 v156, v188
	s_waitcnt lgkmcnt(2)
	v_mfma_f32_32x32x16_bf16 v[66:81], v[70:73], v[114:117], 0
	v_add_u32_e32 v226, s9, v173
	ds_read_b128 v[216:219], v226 offset:16384
	ds_read_b128 v[220:223], v226 offset:24576
	v_exp_f32_e32 v157, v189
	v_exp_f32_e32 v184, v190
	s_waitcnt lgkmcnt(3)
	v_mfma_f32_32x32x16_bf16 v[82:97], v[204:207], v[118:121], v[82:97]
	v_exp_f32_e32 v185, v191
	v_exp_f32_e32 v192, v192
	s_waitcnt lgkmcnt(2)
	v_mfma_f32_32x32x16_bf16 v[66:81], v[208:211], v[118:121], v[66:81]
	v_add_u32_e32 v226, s9, v174
	ds_read_b128 v[204:207], v226 offset:16384
	ds_read_b128 v[208:211], v226 offset:24576
	v_exp_f32_e32 v193, v193
	v_exp_f32_e32 v194, v194
	s_waitcnt lgkmcnt(3)
	v_mfma_f32_32x32x16_bf16 v[82:97], v[216:219], v[126:129], v[82:97]
	v_exp_f32_e32 v195, v195
	v_add_f32_e32 v203, 0, v240
	v_add_f32_e32 v203, v241, v203
	s_waitcnt lgkmcnt(2)
	v_mfma_f32_32x32x16_bf16 v[66:81], v[220:223], v[126:129], v[66:81]
	v_add_u32_e32 v226, s9, v175
	ds_read_b128 v[216:219], v226 offset:16384
	ds_read_b128 v[220:223], v226 offset:24576
	v_exp_f32_e32 v196, v196
	v_add_f32_e32 v203, v242, v203
	v_add_f32_e32 v203, v243, v203
	s_waitcnt lgkmcnt(3)
	v_mfma_f32_32x32x16_bf16 v[82:97], v[204:207], v[122:125], v[82:97]
	v_exp_f32_e32 v197, v197
	v_add_f32_e32 v203, v244, v203
	v_add_f32_e32 v203, v245, v203
	s_waitcnt lgkmcnt(2)
	v_mfma_f32_32x32x16_bf16 v[66:81], v[208:211], v[122:125], v[66:81]
	v_add_u32_e32 v226, s9, v176
	ds_read_b128 v[204:207], v226 offset:16384
	ds_read_b128 v[208:211], v226 offset:24576
	v_exp_f32_e32 v198, v198
	v_add_f32_e32 v203, v246, v203
	v_add_f32_e32 v203, v247, v203
	s_waitcnt lgkmcnt(3)
	v_mfma_f32_32x32x16_bf16 v[82:97], v[216:219], v[110:113], v[82:97]
	v_exp_f32_e32 v199, v199
	v_add_f32_e32 v203, v248, v203
	v_add_f32_e32 v203, v249, v203
	s_waitcnt lgkmcnt(2)
	v_mfma_f32_32x32x16_bf16 v[66:81], v[220:223], v[110:113], v[66:81]
	v_add_u32_e32 v226, s9, v177
	ds_read_b128 v[216:219], v226 offset:16384
	ds_read_b128 v[220:223], v226 offset:24576
	v_exp_f32_e32 v200, v200
	v_add_f32_e32 v203, v250, v203
	v_add_f32_e32 v203, v251, v203
	s_waitcnt lgkmcnt(3)
	v_mfma_f32_32x32x16_bf16 v[82:97], v[204:207], v[106:109], v[82:97]
	v_exp_f32_e32 v201, v201
	v_add_f32_e32 v203, v252, v203
	v_add_f32_e32 v203, v253, v203
	s_waitcnt lgkmcnt(2)
	v_mfma_f32_32x32x16_bf16 v[66:81], v[208:211], v[106:109], v[66:81]
	v_add_u32_e32 v226, s9, v178
	ds_read_b128 v[204:207], v226 offset:16384
	ds_read_b128 v[208:211], v226 offset:24576
	v_exp_f32_e32 v202, v202
	v_add_f32_e32 v203, v254, v203
	v_add_f32_e32 v203, v255, v203
	s_waitcnt lgkmcnt(3)
	v_mfma_f32_32x32x16_bf16 v[82:97], v[216:219], v[102:105], v[82:97]
	v_add_f32_e32 v203, v144, v203
	v_add_f32_e32 v203, v156, v203
	v_cvt_pk_bf16_f32 v130, v240, v241
	s_waitcnt lgkmcnt(2)
; #define MFMA32(a, b, c) __builtin_amdgcn_mfma_f32_32x32x16_bf16((a), (b), (c), 0, 0, 0)
; #define SBAR() __builtin_amdgcn_sched_barrier(0)
; DI void a_qkt(f32x16& p0, f32x16& p1, const char* Ks, const char* Ps, const bf16x8* qr, const char* QP, int r32, int hi) {
;   p0 = f32x16{}; p1 = f32x16{};
; #pragma unroll
;   for (int d0 = 0; d0 < 8; ++d0) { const int cb = (d0 * 16 + hi * 8) * 2;
;     bf16x8 b0 = *reinterpret_cast<const bf16x8*>(Ks + KSWZ(r32, cb));
;     bf16x8 b1 = *reinterpret_cast<const bf16x8*>(Ks + KSWZ(32 + r32, cb));
;     p0 = MFMA32(b0, qr[d0], p0);
;     p1 = MFMA32(b1, qr[d0], p1); }
; #pragma unroll
;   for (int d0 = 0; d0 < 4; ++d0) { const int cb = (d0 * 16 + hi * 8) * 2;
;     bf16x8 b0 = *reinterpret_cast<const bf16x8*>(Ps + PSWZ(r32, cb));
;     bf16x8 b1 = *reinterpret_cast<const bf16x8*>(Ps + PSWZ(32 + r32, cb));
;     const bf16x8 qp = *reinterpret_cast<const bf16x8*>(QP + d0 * 1024);
;     p0 = MFMA32(b0, qp, p0);
;     p1 = MFMA32(b1, qp, p1); }
; }
; DI int v_st(int k, int c) { const int kk = (k & ~0xC) | ((k & 4) << 1) | ((k & 8) >> 1); return ((kk >> 3) * 4 + (c >> 5)) * 512 + ((kk & 7) * 32 + (c & 31)) * 2; }
; DI int v_rd_base(int lane) { return ((lane & 3) << 3) | (((lane >> 2) & 3) << 6) | (((lane >> 4) & 1) << 5) | (((lane >> 5) & 1) << 8); }
; template <int OFF> DI s16x4 tr_read(int vb) {
;   s16x4 r; asm volatile("ds_read_b64_tr_b16 %0, %1 offset:%2" : "=&v"(r) : "v"(vb), "i"(OFF) : "memory"); return r;
; }
; template <int D0> DI void pv_one(f32x16& od, int vb, bf16x8 pa0, bf16x8 pa1, bf16x8 pa2, bf16x8 pa3) {
;   const s16x4 l0 = tr_read<v_rd_off(D0, 0, 0)>(vb), h0 = tr_read<v_rd_off(D0, 0, 1)>(vb), l1 = tr_read<v_rd_off(D0, 1, 0)>(vb), h1 = tr_read<v_rd_off(D0, 1, 1)>(vb);
;   const s16x4 l2 = tr_read<v_rd_off(D0, 2, 0)>(vb), h2 = tr_read<v_rd_off(D0, 2, 1)>(vb), l3 = tr_read<v_rd_off(D0, 3, 0)>(vb), h3 = tr_read<v_rd_off(D0, 3, 1)>(vb);
;   asm volatile("s_waitcnt lgkmcnt(0)" ::: "memory"); SBAR();
;     ...
;   od = MFMA32(pa0, PKV(l0, h0), od);
;   od = MFMA32(pa1, PKV(l1, h1), od);
;   od = MFMA32(pa2, PKV(l2, h2), od);
;   od = MFMA32(pa3, PKV(l3, h3), od);
;     ...
; }
; DI void pv_d0(f32x16* o, int vb, bf16x8 pa0, bf16x8 pa1, bf16x8 pa2, bf16x8 pa3) {
;   pv_one<0>(o[0], vb, pa0, pa1, pa2, pa3); pv_one<1>(o[1], vb, pa0, pa1, pa2, pa3); pv_one<2>(o[2], vb, pa0, pa1, pa2, pa3); pv_one<3>(o[3], vb, pa0, pa1, pa2, pa3);
; }
	v_mfma_f32_32x32x16_bf16 v[66:81], v[220:223], v[102:105], v[66:81]
	v_add_u32_e32 v226, s9, v179
	ds_read_b128 v[216:219], v226 offset:32768
	ds_read_b128 v[220:223], v226 offset:36864
	ds_read_b128 v[228:231], v163
	v_add_f32_e32 v203, v157, v203
	v_add_f32_e32 v203, v184, v203
	v_cvt_pk_bf16_f32 v131, v242, v243
	s_waitcnt lgkmcnt(4)
	v_mfma_f32_32x32x16_bf16 v[82:97], v[204:207], v[98:101], v[82:97]
	v_add_f32_e32 v203, v185, v203
	v_add_f32_e32 v203, v192, v203
	v_cvt_pk_bf16_f32 v132, v244, v245
	s_waitcnt lgkmcnt(3)
	v_mfma_f32_32x32x16_bf16 v[66:81], v[208:211], v[98:101], v[66:81]
	v_add_u32_e32 v226, s9, v180
	ds_read_b128 v[204:207], v226 offset:32768
	ds_read_b128 v[208:211], v226 offset:36864
	ds_read_b128 v[212:215], v163 offset:1024
	v_add_f32_e32 v203, v193, v203
	v_add_f32_e32 v203, v194, v203
	v_cvt_pk_bf16_f32 v133, v246, v247
	s_waitcnt lgkmcnt(3)
	v_mfma_f32_32x32x16_bf16 v[82:97], v[216:219], v[228:231], v[82:97]
	v_add_f32_e32 v203, v195, v203
	v_add_f32_e32 v203, v196, v203
	v_cvt_pk_bf16_f32 v186, v248, v249
	v_mfma_f32_32x32x16_bf16 v[66:81], v[220:223], v[228:231], v[66:81]
	v_add_u32_e32 v226, s9, v181
	ds_read_b128 v[216:219], v226 offset:32768
	ds_read_b128 v[220:223], v226 offset:36864
	ds_read_b128 v[228:231], v163 offset:2048
	v_add_f32_e32 v203, v197, v203
	v_add_f32_e32 v203, v198, v203
	v_cvt_pk_bf16_f32 v187, v250, v251
	s_waitcnt lgkmcnt(3)
	v_mfma_f32_32x32x16_bf16 v[82:97], v[204:207], v[212:215], v[82:97]
	v_add_f32_e32 v203, v199, v203
	v_add_f32_e32 v203, v200, v203
	v_cvt_pk_bf16_f32 v188, v252, v253
	v_mfma_f32_32x32x16_bf16 v[66:81], v[208:211], v[212:215], v[66:81]
	v_add_u32_e32 v226, s9, v182
	ds_read_b128 v[204:207], v226 offset:32768
	ds_read_b128 v[208:211], v226 offset:36864
	ds_read_b128 v[212:215], v163 offset:3072
	v_add_f32_e32 v203, v201, v203
	v_add_f32_e32 v154, v202, v203
	v_cvt_pk_bf16_f32 v189, v254, v255
	s_waitcnt lgkmcnt(3)
	v_mfma_f32_32x32x16_bf16 v[82:97], v[216:219], v[228:231], v[82:97]
	v_mov_b32_e32 v155, v154
	v_cvt_pk_bf16_f32 v190, v144, v156
	v_cvt_pk_bf16_f32 v191, v157, v184
	v_permlane32_swap_b32_e32 v130, v132
	v_mfma_f32_32x32x16_bf16 v[66:81], v[220:223], v[228:231], v[66:81]
	v_add_u32_e32 v232, s7, v171
	ds_read_b64_tr_b16 v[216:217], v232 offset:2048
	ds_read_b64_tr_b16 v[218:219], v232 offset:4096
	ds_read_b64_tr_b16 v[220:221], v232 offset:6144
	ds_read_b64_tr_b16 v[222:223], v232 offset:8192
	ds_read_b64_tr_b16 v[224:225], v232 offset:10240
	ds_read_b64_tr_b16 v[226:227], v232 offset:12288
	ds_read_b64_tr_b16 v[228:229], v232 offset:14336
	v_cvt_pk_bf16_f32 v192, v185, v192
	v_cvt_pk_bf16_f32 v193, v193, v194
	v_permlane32_swap_b32_e32 v154, v155
	v_permlane32_swap_b32_e32 v131, v133
	s_waitcnt lgkmcnt(7)
	v_mfma_f32_32x32x16_bf16 v[82:97], v[204:207], v[212:215], v[82:97]
	v_cvt_pk_bf16_f32 v194, v195, v196
	v_cvt_pk_bf16_f32 v195, v197, v198
	v_permlane32_swap_b32_e32 v186, v188
	v_mfma_f32_32x32x16_bf16 v[66:81], v[208:211], v[212:215], v[66:81]
	ds_read_b64_tr_b16 v[214:215], v232 offset:0
	v_cvt_pk_bf16_f32 v196, v199, v200
	v_cvt_pk_bf16_f32 v197, v201, v202
	v_permlane32_swap_b32_e32 v187, v189
	s_nop 0
	v_permlane32_swap_b32_e32 v190, v192
	v_permlane32_swap_b32_e32 v191, v193
	v_permlane32_swap_b32_e32 v194, v196
	v_permlane32_swap_b32_e32 v195, v197
	v_add_co_u32_e32 v156, vcc, s59, v146
	s_nop 1
	v_addc_co_u32_e32 v157, vcc, 0, v147, vcc
	v_add_co_u32_e32 v146, vcc, s60, v146
	s_nop 1
	v_addc_co_u32_e32 v147, vcc, 0, v147, vcc
	global_load_dwordx4 v[198:201], v[156:157], off offset:256
	global_load_dwordx4 v[202:205], v[156:157], off
	global_load_dwordx4 v[206:209], v[146:147], off offset:256
	global_load_dwordx4 v[210:213], v[146:147], off
	v_add_co_u32_e32 v146, vcc, s61, v148
	s_nop 1
	v_addc_co_u32_e32 v147, vcc, 0, v149, vcc
	global_load_dwordx4 v[146:149], v[146:147], off
	v_add_u32_e32 v156, s7, v171
	s_waitcnt lgkmcnt(0)
	s_nop 0
	v_mfma_f32_32x32x16_bf16 v[2:17], v[130:133], v[214:217], v[2:17]
	ds_read_b64_tr_b16 v[214:215], v156 offset:0x200
	ds_read_b64_tr_b16 v[216:217], v156 offset:0xa00
	v_max_f32_e32 v144, v83, v83
	v_max_f32_e32 v157, v82, v82
	v_max_f32_e32 v144, v157, v144
	v_max3_f32 v144, v144, v84, v85
	v_max3_f32 v144, v144, v86, v87
	v_mfma_f32_32x32x16_bf16 v[2:17], v[186:189], v[218:221], v[2:17]
	ds_read_b64_tr_b16 v[218:219], v156 offset:0x1200
	ds_read_b64_tr_b16 v[220:221], v156 offset:0x1a00
	v_max3_f32 v144, v144, v88, v89
	v_max3_f32 v144, v144, v90, v91
	v_max3_f32 v144, v144, v92, v93
	v_max3_f32 v144, v144, v94, v95
	v_max3_f32 v144, v144, v96, v97
	v_mfma_f32_32x32x16_bf16 v[2:17], v[190:193], v[222:225], v[2:17]
	ds_read_b64_tr_b16 v[222:223], v156 offset:0x2200
	ds_read_b64_tr_b16 v[224:225], v156 offset:0x2a00
	ds_read_b64_tr_b16 v[230:231], v156 offset:0x3200
	ds_read_b64_tr_b16 v[232:233], v156 offset:0x3a00
	v_mfma_f32_32x32x16_bf16 v[2:17], v[194:197], v[226:229], v[2:17]
	s_waitcnt lgkmcnt(0)
; #define SBAR() __builtin_amdgcn_sched_barrier(0)
; #define SWAIT() asm volatile("s_waitcnt vmcnt(0)" ::: "memory")
; DI void pv_sm(f32x16* o, int vb, bf16x8 pa0, bf16x8 pa1, bf16x8 pa2, bf16x8 pa3, f32x16& p0, f32x16& p1, float& m_reg, float& mn, float& alpha) {
;   PV_BLOCK(0)
;   float pm0 = p0[0];
; #pragma unroll
;   for (int r = 1; r < 16; ++r) pm0 = fmaxf(pm0, p0[r]);
;   PV_BLOCK(1)
;   float pmax = pm0;
; #pragma unroll
;   for (int r = 0; r < 16; ++r) pmax = fmaxf(pmax, p1[r]);
;   { auto rr = __builtin_amdgcn_permlane32_swap(__float_as_uint(pmax), __float_as_uint(pmax), false, false);
;     pmax = fmaxf(__uint_as_float(rr[0]), __uint_as_float(rr[1])); }
;   const bool keep = __all(pmax - m_reg <= ATH);
;   mn = keep ? m_reg : fmaxf(m_reg, pmax);
;   alpha = __builtin_amdgcn_exp2f(m_reg - mn);
;   m_reg = mn;
;   PV_BLOCK(2)
; #pragma unroll
;   for (int r = 0; r < 16; ++r) { p0[r] = p0[r] - mn; p1[r] = p1[r] - mn; }
;   PV_BLOCK(3)
; #pragma unroll
;   for (int r = 0; r < 16; ++r) p0[r] = __builtin_amdgcn_exp2f(p0[r]);
; }
; DI void attn_unit(const bf16_t* __restrict__ Qb, const bf16_t* __restrict__ Kh, const bf16_t* __restrict__ Vh, const bf16_t* __restrict__ Ph,
;                   bf16_t* __restrict__ Ob, int seq, float* __restrict__ lse_out, char* lds) {
;     ...
;   f32x16 pA0, pA1, pB0, pB1; float mnA, mnB, alA, alB; bf16x8 pa0, pa1, pa2, pa3; const int NT = seq / 64;
;   SLOAD(0); SWAIT(); SWRITE(0); __syncthreads();
;   a_qkt(pA0, pA1, lds + A_KO, lds + A_PO, qr, QP, r32, hi); a_partialSM(pA0, pA1, m_reg, mnA, alA);
;   SLOAD(64);
;   SWAIT(); SWRITE(A_STG); __syncthreads();
;   int sV = 0, sK = A_STG, sW = 2 * A_STG;
;   for (int j = 1; j + 1 < NT; j += 2) {
;     SBAR(); a_qkt(pB0, pB1, lds + sK + A_KO, lds + sK + A_PO, qr, QP, r32, hi);
;     a_finishSM(pA0, pA1, alA, l_reg, pa0, pa1, pa2, pa3); SBAR();
;     SLOAD((j + 1) * 64); SBAR();
;     pv_sm(o, vb0 + sV, pa0, pa1, pa2, pa3, pB0, pB1, m_reg, mnB, alB);
;     SWAIT(); SWRITE(sW);
;     RESC(alB); __syncthreads();
;     { const int t_ = sV; sV = sK; sK = sW; sW = t_; }
;     SBAR(); a_qkt(pA0, pA1, lds + sK + A_KO, lds + sK + A_PO, qr, QP, r32, hi);
;     a_finishSM(pB0, pB1, alB, l_reg, pa0, pa1, pa2, pa3); SBAR();
;     SLOAD((j + 2) * 64); SBAR();
;     pv_sm(o, vb0 + sV, pa0, pa1, pa2, pa3, pA0, pA1, m_reg, mnA, alA);
;     SWAIT(); SWRITE(sW);
;     RESC(alA); __syncthreads();
	v_mfma_f32_32x32x16_bf16 v[50:65], v[130:133], v[214:217], v[50:65]
	v_max3_f32 v144, v144, v66, v67
	v_max3_f32 v144, v144, v68, v69
	v_max3_f32 v144, v144, v70, v71
	v_max3_f32 v144, v144, v72, v73
	v_max3_f32 v144, v144, v74, v75
	v_max3_f32 v144, v144, v76, v77
	v_max3_f32 v144, v144, v78, v79
	v_mfma_f32_32x32x16_bf16 v[50:65], v[186:189], v[218:221], v[50:65]
	v_max3_f32 v144, v144, v80, v81
	v_mov_b32_e32 v157, v144
	s_nop 1
	v_permlane32_swap_b32_e32 v144, v157
	v_max_f32_e32 v157, v157, v157
	v_max_f32_e32 v144, v144, v144
	v_max_f32_e32 v144, v144, v157
	v_mfma_f32_32x32x16_bf16 v[50:65], v[190:193], v[222:225], v[50:65]
	ds_read_b64_tr_b16 v[214:215], v156 offset:0x400
	v_sub_f32_e32 v157, v144, v153
	ds_read_b64_tr_b16 v[216:217], v156 offset:0xc00
	v_cmp_ge_f32_e32 vcc, s54, v157
	ds_read_b64_tr_b16 v[218:219], v156 offset:0x1400
	s_cmp_eq_u64 vcc, exec
	v_max_f32_e32 v157, v153, v153
	ds_read_b64_tr_b16 v[220:221], v156 offset:0x1c00
	ds_read_b64_tr_b16 v[222:223], v156 offset:0x2400
	ds_read_b64_tr_b16 v[224:225], v156 offset:0x2c00
	ds_read_b64_tr_b16 v[226:227], v156 offset:0x3400
	ds_read_b64_tr_b16 v[228:229], v156 offset:0x3c00
	v_mfma_f32_32x32x16_bf16 v[50:65], v[194:197], v[230:233], v[50:65]
	v_max_f32_e32 v144, v157, v144
	s_cselect_b64 vcc, -1, 0
	v_cndmask_b32_e32 v144, v144, v153, vcc
	v_sub_f32_e32 v153, v153, v144
	v_exp_f32_e32 v184, v153
	s_waitcnt lgkmcnt(0)
	v_mfma_f32_32x32x16_bf16 v[34:49], v[130:133], v[214:217], v[34:49]
	ds_read_b64_tr_b16 v[214:215], v156 offset:0x600
	ds_read_b64_tr_b16 v[216:217], v156 offset:0xe00
	v_sub_f32_e32 v82, v82, v144
	v_sub_f32_e32 v83, v83, v144
	v_sub_f32_e32 v84, v84, v144
	v_sub_f32_e32 v85, v85, v144
	v_mfma_f32_32x32x16_bf16 v[34:49], v[186:189], v[218:221], v[34:49]
	ds_read_b64_tr_b16 v[218:219], v156 offset:0x1600
	ds_read_b64_tr_b16 v[220:221], v156 offset:0x1e00
	v_sub_f32_e32 v86, v86, v144
	v_sub_f32_e32 v87, v87, v144
	v_exp_f32_e32 v240, v82
	v_exp_f32_e32 v241, v83
	v_mfma_f32_32x32x16_bf16 v[34:49], v[190:193], v[222:225], v[34:49]
	ds_read_b64_tr_b16 v[222:223], v156 offset:0x2600
	ds_read_b64_tr_b16 v[224:225], v156 offset:0x2e00
	ds_read_b64_tr_b16 v[230:231], v156 offset:0x3600
	ds_read_b64_tr_b16 v[232:233], v156 offset:0x3e00
	v_mfma_f32_32x32x16_bf16 v[34:49], v[194:197], v[226:229], v[34:49]
	v_sub_f32_e32 v88, v88, v144
	v_sub_f32_e32 v89, v89, v144
	v_exp_f32_e32 v242, v84
	v_exp_f32_e32 v243, v85
	s_waitcnt lgkmcnt(0)
	v_sub_f32_e32 v90, v90, v144
	v_sub_f32_e32 v91, v91, v144
	v_exp_f32_e32 v244, v86
	v_exp_f32_e32 v245, v87
	v_mfma_f32_32x32x16_bf16 v[18:33], v[130:133], v[214:217], v[18:33]
	v_sub_f32_e32 v92, v92, v144
	v_sub_f32_e32 v93, v93, v144
	v_exp_f32_e32 v246, v88
	v_exp_f32_e32 v247, v89
	s_add_i32 s9, s8, 0
	v_add_u32_e32 v130, s9, v164
	s_waitcnt vmcnt(0)
	ds_write_b128 v130, v[198:201]
	v_add_u32_e32 v130, s9, v165
	ds_write_b128 v130, v[206:209]
	v_add_u32_e32 v130, s9, v167
	v_mfma_f32_32x32x16_bf16 v[18:33], v[186:189], v[218:221], v[18:33]
	ds_write_b128 v130, v[202:205] offset:16384
	v_add_u32_e32 v130, s9, v168
	ds_write_b128 v130, v[210:213] offset:16384
	v_add_u32_e32 v130, s9, v169
	v_cmp_gt_f32_e32 vcc, 1.0, v184
	ds_write_b128 v130, v[146:149] offset:32768
	v_sub_f32_e32 v94, v94, v144
	v_sub_f32_e32 v95, v95, v144
	v_exp_f32_e32 v248, v90
	v_exp_f32_e32 v249, v91
	v_mfma_f32_32x32x16_bf16 v[18:33], v[190:193], v[222:225], v[18:33]
	v_sub_f32_e32 v96, v96, v144
	v_sub_f32_e32 v97, v97, v144
	v_exp_f32_e32 v250, v92
	v_exp_f32_e32 v251, v93
	v_mfma_f32_32x32x16_bf16 v[18:33], v[194:197], v[230:233], v[18:33]
	v_exp_f32_e32 v252, v94
	v_exp_f32_e32 v253, v95
	v_exp_f32_e32 v254, v96
	v_exp_f32_e32 v255, v97
	s_cbranch_vccz .LBB0_673
	s_and_saveexec_b64 s[4:5], s[2:3]
	ds_write_b32 v161, v184 offset:128
	s_or_b64 exec, exec, s[4:5]
	s_waitcnt lgkmcnt(0)
	v_add_u32_e32 v153, v137, v134
	ds_read_b128 v[130:133], v153 offset:224
	ds_read_b128 v[146:149], v153 offset:192
	ds_read_b128 v[186:189], v153 offset:160
	ds_read_b128 v[190:193], v153 offset:128
	s_waitcnt lgkmcnt(3)
	v_pk_mul_f32 v[14:15], v[14:15], v[130:131]
	s_waitcnt lgkmcnt(2)
	v_pk_mul_f32 v[10:11], v[10:11], v[146:147]
	s_waitcnt lgkmcnt(1)
	v_pk_mul_f32 v[6:7], v[6:7], v[186:187]
	v_pk_mul_f32 v[16:17], v[16:17], v[132:133]
	v_pk_mul_f32 v[12:13], v[12:13], v[148:149]
	v_pk_mul_f32 v[8:9], v[8:9], v[188:189]
	s_waitcnt lgkmcnt(0)
	v_pk_mul_f32 v[4:5], v[4:5], v[192:193]
	v_pk_mul_f32 v[2:3], v[2:3], v[190:191]
	v_pk_mul_f32 v[62:63], v[62:63], v[130:131]
	v_pk_mul_f32 v[58:59], v[58:59], v[146:147]
	v_pk_mul_f32 v[54:55], v[54:55], v[186:187]
	v_pk_mul_f32 v[64:65], v[64:65], v[132:133]
	v_pk_mul_f32 v[60:61], v[60:61], v[148:149]
	v_pk_mul_f32 v[56:57], v[56:57], v[188:189]
	v_pk_mul_f32 v[52:53], v[52:53], v[192:193]
	v_pk_mul_f32 v[50:51], v[50:51], v[190:191]
	v_pk_mul_f32 v[46:47], v[46:47], v[130:131]
	v_pk_mul_f32 v[42:43], v[42:43], v[146:147]
	v_pk_mul_f32 v[38:39], v[38:39], v[186:187]
	v_pk_mul_f32 v[48:49], v[48:49], v[132:133]
	v_pk_mul_f32 v[44:45], v[44:45], v[148:149]
	v_pk_mul_f32 v[40:41], v[40:41], v[188:189]
	v_pk_mul_f32 v[36:37], v[36:37], v[192:193]
	v_pk_mul_f32 v[34:35], v[34:35], v[190:191]
	v_pk_mul_f32 v[30:31], v[30:31], v[130:131]
	v_pk_mul_f32 v[26:27], v[26:27], v[146:147]
	v_pk_mul_f32 v[22:23], v[22:23], v[186:187]
	v_pk_mul_f32 v[32:33], v[32:33], v[132:133]
	v_pk_mul_f32 v[28:29], v[28:29], v[148:149]
	v_pk_mul_f32 v[24:25], v[24:25], v[188:189]
	v_pk_mul_f32 v[20:21], v[20:21], v[192:193]
	v_pk_mul_f32 v[18:19], v[18:19], v[190:191]
